# speedup vs baseline: 1.0048x; 1.0048x over previous
; __device__ __forceinline__ unsigned pk2(float lo, float hi) { const f32x2_t v = {lo, hi}; return __builtin_bit_cast(unsigned, __builtin_convertvector(v, bf16x2_t)); }
;     const int r_beg = gw, r_end = nrows;
;     int cur_mod = -1; f32x4 gs[4], shv[4], vn[4];
; #pragma unroll
;     for (int j = 0; j < 4; ++j) { gs[j] = (f32x4){0.f, 0.f, 0.f, 0.f}; shv[j] = gs[j]; vn[j] = gs[j]; }
;     if (r_beg < r_end) {
; #pragma unroll
;         for (int j = 0; j < 4; ++j) vn[j] = ld_row4(srcL, xb_in, srcC, r_beg, lane + 64 * j); }
; #pragma unroll 1
;     for (int row = r_beg; row < r_end; row += NGW) {
;         const bool isc = row >= ML; const int mod = isc ? 4 : (row >> 13);
;         f32x4 v[4];
; #pragma unroll
;         for (int j = 0; j < 4; ++j) v[j] = vn[j];
;         if (row + NGW < r_end) { const int rn = row + NGW;
; #pragma unroll
;             for (int j = 0; j < 4; ++j) vn[j] = ld_row4(srcL, xb_in, srcC, rn, lane + 64 * j); }
;         if (xb_out && !isc) {
; #pragma unroll
;             for (int j = 0; j < 4; ++j) { u32x2 w; w.x = pk2(v[j].x, v[j].y); w.y = pk2(v[j].z, v[j].w); ((u32x2*)(xb_out + (size_t)row * DM))[lane + 64 * j] = w; } }
;         if (mod != cur_mod) { cur_mod = mod; const float* shp = mods_l + mod * 6144 + sh_off; const float* scp = mods_l + mod * 6144 + sc_off;
; #pragma unroll
;             for (int j = 0; j < 4; ++j) { gs[j] = ((const f32x4*)gam)[lane + 64 * j] * (((const f32x4*)scp)[lane + 64 * j] + 1.0f); shv[j] = ((const f32x4*)shp)[lane + 64 * j]; } }
.Ln7_begin:
	v_lshlrev_b32_e32 v86, 4, v249
	v_lshlrev_b32_e32 v74, 5, v249
	v_lshlrev_b32_e32 v3, 2, v249
	v_xor_b32_e32 v1, 4, v3
	v_xor_b32_e32 v71, 8, v3
	v_xor_b32_e32 v73, 16, v3
	v_xor_b32_e32 v96, 32, v3
	v_xor_b32_e32 v97, 64, v3
	v_xor_b32_e32 v98, 0x80, v3
	s_load_dwordx2 s[0:1], s[28:29], 0x30
	s_lshl_b32 s6, s22, 12
	s_waitcnt lgkmcnt(0)
	s_add_u32 s0, s0, s6
	s_addc_u32 s1, s1, 0
	s_add_u32 s0, s0, 0x1000
	s_addc_u32 s1, s1, 0
	s_mov_b32 s3, -1
	s_mov_b32 s8, s10
	s_lshl_b32 s13, s12, 11
	s_cmp_lt_i32 s8, 0x8000
	s_cbranch_scc0 .Ln7_ctx
	s_ashr_i32 s11, s10, 31
	s_lshl_b64 s[6:7], s[10:11], 11
	s_add_u32 s34, s30, s6
	s_addc_u32 s35, s31, s7
	s_add_u32 s36, s75, s6
	s_addc_u32 s37, s76, s7
	s_mov_b32 s46, s10
	global_load_dwordx4 v[100:103], v86, s[34:35]
	global_load_dwordx4 v[104:107], v86, s[34:35] offset:1024
	s_add_i32 s11, s46, s12
	s_cmp_lt_i32 s11, 0x8000
	s_cselect_b32 s46, s11, s46
	s_cselect_b32 s11, s13, 0
	s_add_u32 s34, s34, s11
	s_addc_u32 s35, s35, 0
	global_load_dwordx4 v[108:111], v86, s[34:35]
	global_load_dwordx4 v[112:115], v86, s[34:35] offset:1024
	s_add_i32 s11, s46, s12
	s_cmp_lt_i32 s11, 0x8000
	s_cselect_b32 s46, s11, s46
	s_cselect_b32 s11, s13, 0
	s_add_u32 s34, s34, s11
	s_addc_u32 s35, s35, 0
	s_waitcnt vmcnt(2)
	v_lshlrev_b32_e32 v54, 16, v100
	v_and_b32_e32 v55, 0xffff0000, v100
	v_lshlrev_b32_e32 v56, 16, v101
	v_and_b32_e32 v57, 0xffff0000, v101
	v_lshlrev_b32_e32 v58, 16, v102
	v_and_b32_e32 v59, 0xffff0000, v102
	v_lshlrev_b32_e32 v60, 16, v103
	v_and_b32_e32 v61, 0xffff0000, v103
	v_lshlrev_b32_e32 v62, 16, v104
	v_and_b32_e32 v63, 0xffff0000, v104
	v_lshlrev_b32_e32 v64, 16, v105
	v_and_b32_e32 v65, 0xffff0000, v105
	v_lshlrev_b32_e32 v66, 16, v106
	v_and_b32_e32 v67, 0xffff0000, v106
	v_lshlrev_b32_e32 v68, 16, v107
	v_and_b32_e32 v69, 0xffff0000, v107
.Ln7_loopA:
	s_ashr_i32 s11, s8, 13
	s_cmp_eq_u32 s11, s3
	s_cbranch_scc1 .Ln7_modokA
	s_mov_b32 s3, s11
	s_mul_i32 s11, s11, 0x6000
	s_add_u32 s42, s80, s11
	s_addc_u32 s43, s81, 0
	s_add_u32 s54, s42, 0x1e000
	s_addc_u32 s55, s43, 0
	s_add_u32 s42, s42, 0x1f000
	s_addc_u32 s43, s43, 0
	global_load_dwordx4 v[10:13], v74, s[42:43]
	global_load_dwordx4 v[18:21], v74, s[42:43] offset:16
	global_load_dwordx4 v[30:33], v74, s[42:43] offset:2048
	global_load_dwordx4 v[46:49], v74, s[42:43] offset:2064
	global_load_dwordx4 v[6:9], v74, s[0:1]
	global_load_dwordx4 v[14:17], v74, s[0:1] offset:16
	global_load_dwordx4 v[26:29], v74, s[0:1] offset:2048
	global_load_dwordx4 v[38:41], v74, s[0:1] offset:2064
	s_waitcnt vmcnt(0)
	v_pk_add_f32 v[10:11], v[10:11], 1.0 op_sel_hi:[1,0]
	v_pk_add_f32 v[12:13], v[12:13], 1.0 op_sel_hi:[1,0]
	v_pk_mul_f32 v[6:7], v[6:7], v[10:11]
	v_pk_mul_f32 v[8:9], v[8:9], v[12:13]
	v_pk_add_f32 v[18:19], v[18:19], 1.0 op_sel_hi:[1,0]
	v_pk_add_f32 v[20:21], v[20:21], 1.0 op_sel_hi:[1,0]
	v_pk_mul_f32 v[14:15], v[14:15], v[18:19]
	v_pk_mul_f32 v[16:17], v[16:17], v[20:21]
	v_pk_add_f32 v[30:31], v[30:31], 1.0 op_sel_hi:[1,0]
	v_pk_add_f32 v[32:33], v[32:33], 1.0 op_sel_hi:[1,0]
	v_pk_mul_f32 v[26:27], v[26:27], v[30:31]
	v_pk_mul_f32 v[28:29], v[28:29], v[32:33]
	v_pk_add_f32 v[46:47], v[46:47], 1.0 op_sel_hi:[1,0]
	v_pk_add_f32 v[48:49], v[48:49], 1.0 op_sel_hi:[1,0]
	v_pk_mul_f32 v[38:39], v[38:39], v[46:47]
	v_pk_mul_f32 v[40:41], v[40:41], v[48:49]
	global_load_dwordx4 v[10:13], v74, s[54:55]
	global_load_dwordx4 v[18:21], v74, s[54:55] offset:16
	global_load_dwordx4 v[30:33], v74, s[54:55] offset:2048
	global_load_dwordx4 v[46:49], v74, s[54:55] offset:2064
; __device__ __forceinline__ unsigned pk2(float lo, float hi) { const f32x2_t v = {lo, hi}; return __builtin_bit_cast(unsigned, __builtin_convertvector(v, bf16x2_t)); }
;     ...
;     for (int row = r_beg; row < r_end; row += NGW) {
;         const bool isc = row >= ML; const int mod = isc ? 4 : (row >> 13);
;         f32x4 v[4];
; #pragma unroll
;         for (int j = 0; j < 4; ++j) v[j] = vn[j];
;         if (row + NGW < r_end) { const int rn = row + NGW;
; #pragma unroll
;             for (int j = 0; j < 4; ++j) vn[j] = ld_row4(srcL, xb_in, srcC, rn, lane + 64 * j); }
;         if (xb_out && !isc) {
; #pragma unroll
;             for (int j = 0; j < 4; ++j) { u32x2 w; w.x = pk2(v[j].x, v[j].y); w.y = pk2(v[j].z, v[j].w); ((u32x2*)(xb_out + (size_t)row * DM))[lane + 64 * j] = w; } }
;         if (mod != cur_mod) { cur_mod = mod; const float* shp = mods_l + mod * 6144 + sh_off; const float* scp = mods_l + mod * 6144 + sc_off;
; #pragma unroll
;             for (int j = 0; j < 4; ++j) { gs[j] = ((const f32x4*)gam)[lane + 64 * j] * (((const f32x4*)scp)[lane + 64 * j] + 1.0f); shv[j] = ((const f32x4*)shp)[lane + 64 * j]; } }
;         if (isc && npart > 0) {
;             for (int ks = 0; ks < npart; ++ks) { const f32x4* pp = (const f32x4*)(part + ((size_t)ks * MC + (row - ML)) * DM);
; #pragma unroll
;                 for (int j = 0; j < 4; ++j) v[j] += pp[lane + 64 * j]; }
; #pragma unroll
;             for (int j = 0; j < 4; ++j) ((f32x4*)(srcC + (size_t)(row - ML) * DM))[lane + 64 * j] = v[j];
;         }
;         float s = 0.f;
; #pragma unroll
;         for (int j = 0; j < 4; ++j) s += (v[j].x * v[j].x + v[j].y * v[j].y) + (v[j].z * v[j].z + v[j].w * v[j].w);
;         s = wave_sum(s, lane); const float rstd = 1.0f / sqrtf(s * (1.0f / DM) + 1e-6f);
; #pragma unroll
;         for (int j = 0; j < 4; ++j) { const f32x4 y = v[j] * rstd * gs[j] + shv[j]; u32x2 w; w.x = pk2(y.x, y.y); w.y = pk2(y.z, y.w);
;             ((u32x2*)(H + (size_t)row * DM))[lane + 64 * j] = w; }
.Ln7_modokA:
	global_load_dwordx4 v[100:103], v86, s[34:35]
	global_load_dwordx4 v[104:107], v86, s[34:35] offset:1024
	s_add_i32 s11, s46, s12
	s_cmp_lt_i32 s11, 0x8000
	s_cselect_b32 s46, s11, s46
	s_cselect_b32 s11, s13, 0
	s_add_u32 s34, s34, s11
	s_addc_u32 s35, s35, 0
	v_pk_mul_f32 v[90:91], v[56:57], v[56:57]
	v_pk_mul_f32 v[92:93], v[54:55], v[54:55]
	v_pk_mul_f32 v[4:5], v[60:61], v[60:61]
	v_pk_mul_f32 v[88:89], v[58:59], v[58:59]
	v_pk_mov_b32 v[94:95], v[92:93], v[90:91] op_sel:[1,0]
	v_mov_b32_e32 v93, v91
	v_pk_add_f32 v[90:91], v[94:95], v[92:93]
	v_pk_mov_b32 v[92:93], v[88:89], v[4:5] op_sel:[1,0]
	v_mov_b32_e32 v89, v5
	v_pk_add_f32 v[4:5], v[92:93], v[88:89]
	v_pk_add_f32 v[90:91], v[90:91], v[90:91] op_sel_hi:[0,1]
	v_pk_add_f32 v[4:5], v[4:5], v[4:5] op_sel_hi:[0,1]
	v_mul_f32_e32 v4, v62, v62
	v_pk_fma_f32 v[88:89], v[62:63], v[62:63], v[4:5] op_sel_hi:[1,1,0]
	v_mul_f32_e32 v4, v64, v64
	v_pk_fma_f32 v[92:93], v[64:65], v[64:65], v[4:5] op_sel_hi:[1,1,0]
	v_mul_f32_e32 v88, v66, v66
	v_mul_f32_e32 v92, v67, v67
	v_mul_f32_e32 v90, v68, v68
	v_mul_f32_e32 v4, v69, v69
	v_pk_add_f32 v[88:89], v[88:89], v[92:93]
	v_pk_add_f32 v[4:5], v[90:91], v[4:5]
	v_pk_add_f32 v[4:5], v[88:89], v[4:5]
	s_nop 0
	v_add_f32_e32 v3, v4, v5
	ds_bpermute_b32 v4, v1, v3
	s_waitcnt lgkmcnt(0)
	v_add_f32_e32 v3, v3, v4
	ds_bpermute_b32 v4, v71, v3
	s_waitcnt lgkmcnt(0)
	v_add_f32_e32 v3, v3, v4
	ds_bpermute_b32 v4, v73, v3
	s_waitcnt lgkmcnt(0)
	v_add_f32_e32 v3, v3, v4
	ds_bpermute_b32 v4, v96, v3
	s_waitcnt lgkmcnt(0)
	v_add_f32_e32 v3, v3, v4
	ds_bpermute_b32 v4, v97, v3
	s_waitcnt lgkmcnt(0)
	v_add_f32_e32 v3, v3, v4
	ds_bpermute_b32 v4, v98, v3
	s_waitcnt lgkmcnt(0)
	v_add_f32_e32 v3, v3, v4
	v_fmamk_f32 v3, v3, 0x3a800000, v238
	v_mul_f32_e32 v4, 0x4f800000, v3
	v_cmp_gt_f32_e32 vcc, s58, v3
	s_nop 1
	v_cndmask_b32_e32 v3, v3, v4, vcc
	v_sqrt_f32_e32 v4, v3
	s_nop 0
	v_add_u32_e32 v5, -1, v4
	v_add_u32_e32 v75, 1, v4
	v_fma_f32 v88, -v5, v4, v3
	v_fma_f32 v89, -v75, v4, v3
	v_cmp_ge_f32_e64 s[4:5], 0, v88
	s_nop 1
	v_cndmask_b32_e64 v4, v4, v5, s[4:5]
	v_cmp_lt_f32_e64 s[4:5], 0, v89
	s_nop 1
	v_cndmask_b32_e64 v4, v4, v75, s[4:5]
	v_mul_f32_e32 v5, 0x37800000, v4
	v_cndmask_b32_e32 v4, v4, v5, vcc
	v_cmp_class_f32_e32 vcc, v3, v248
	s_nop 1
	v_cndmask_b32_e32 v3, v4, v3, vcc
	v_div_scale_f32 v75, s[4:5], v3, v3, 1.0
	v_rcp_f32_e32 v88, v75
	v_div_scale_f32 v89, vcc, 1.0, v3, 1.0
	v_fma_f32 v90, -v75, v88, 1.0
	v_fmac_f32_e32 v88, v90, v88
	v_mul_f32_e32 v90, v89, v88
	v_fma_f32 v91, -v75, v90, v89
	v_fmac_f32_e32 v90, v91, v88
	v_fma_f32 v75, -v75, v90, v89
	v_div_fmas_f32 v75, v75, v88, v90
	v_div_fixup_f32 v88, v75, v3, 1.0
	s_waitcnt vmcnt(2)
	v_pk_mul_f32 v[54:55], v[54:55], v[88:89] op_sel_hi:[1,0]
	v_pk_mul_f32 v[56:57], v[56:57], v[88:89] op_sel_hi:[1,0]
	v_pk_fma_f32 v[54:55], v[6:7], v[54:55], v[10:11]
	v_pk_fma_f32 v[56:57], v[8:9], v[56:57], v[12:13]
	v_cvt_pk_bf16_f32 v120, v54, v55
	v_cvt_pk_bf16_f32 v121, v56, v57
	v_pk_mul_f32 v[58:59], v[58:59], v[88:89] op_sel_hi:[1,0]
	v_pk_mul_f32 v[60:61], v[60:61], v[88:89] op_sel_hi:[1,0]
	v_pk_fma_f32 v[58:59], v[14:15], v[58:59], v[18:19]
	v_pk_fma_f32 v[60:61], v[16:17], v[60:61], v[20:21]
	v_cvt_pk_bf16_f32 v122, v58, v59
	v_cvt_pk_bf16_f32 v123, v60, v61
	global_store_dwordx4 v86, v[120:123], s[36:37]
	v_pk_mul_f32 v[62:63], v[62:63], v[88:89] op_sel_hi:[1,0]
	v_pk_mul_f32 v[64:65], v[64:65], v[88:89] op_sel_hi:[1,0]
	v_pk_fma_f32 v[62:63], v[26:27], v[62:63], v[30:31]
	v_pk_fma_f32 v[64:65], v[28:29], v[64:65], v[32:33]
	v_cvt_pk_bf16_f32 v124, v62, v63
	v_cvt_pk_bf16_f32 v125, v64, v65
	v_pk_mul_f32 v[66:67], v[66:67], v[88:89] op_sel_hi:[1,0]
	v_pk_mul_f32 v[68:69], v[68:69], v[88:89] op_sel_hi:[1,0]
	v_pk_fma_f32 v[66:67], v[38:39], v[66:67], v[46:47]
	v_pk_fma_f32 v[68:69], v[40:41], v[68:69], v[48:49]
	v_cvt_pk_bf16_f32 v126, v66, v67
	v_cvt_pk_bf16_f32 v127, v68, v69
	global_store_dwordx4 v86, v[124:127], s[36:37] offset:1024
	v_lshlrev_b32_e32 v54, 16, v108
	v_and_b32_e32 v55, 0xffff0000, v108
	v_lshlrev_b32_e32 v56, 16, v109
	v_and_b32_e32 v57, 0xffff0000, v109
	v_lshlrev_b32_e32 v58, 16, v110
	v_and_b32_e32 v59, 0xffff0000, v110
	v_lshlrev_b32_e32 v60, 16, v111
	v_and_b32_e32 v61, 0xffff0000, v111
	v_lshlrev_b32_e32 v62, 16, v112
	v_and_b32_e32 v63, 0xffff0000, v112
	v_lshlrev_b32_e32 v64, 16, v113
	v_and_b32_e32 v65, 0xffff0000, v113
	v_lshlrev_b32_e32 v66, 16, v114
	v_and_b32_e32 v67, 0xffff0000, v114
	v_lshlrev_b32_e32 v68, 16, v115
	v_and_b32_e32 v69, 0xffff0000, v115
	s_add_i32 s8, s8, s12
	s_add_u32 s36, s36, s13
	s_addc_u32 s37, s37, 0
	s_cmp_lt_i32 s8, 0x8000
	s_cbranch_scc0 .Ln7_ctx

; __device__ __forceinline__ unsigned pk2(float lo, float hi) { const f32x2_t v = {lo, hi}; return __builtin_bit_cast(unsigned, __builtin_convertvector(v, bf16x2_t)); }
;     ...
;     for (int row = r_beg; row < r_end; row += NGW) {
;         const bool isc = row >= ML; const int mod = isc ? 4 : (row >> 13);
;         f32x4 v[4];
; #pragma unroll
;         for (int j = 0; j < 4; ++j) v[j] = vn[j];
;         if (row + NGW < r_end) { const int rn = row + NGW;
; #pragma unroll
;             for (int j = 0; j < 4; ++j) vn[j] = ld_row4(srcL, xb_in, srcC, rn, lane + 64 * j); }
;         if (xb_out && !isc) {
; #pragma unroll
;             for (int j = 0; j < 4; ++j) { u32x2 w; w.x = pk2(v[j].x, v[j].y); w.y = pk2(v[j].z, v[j].w); ((u32x2*)(xb_out + (size_t)row * DM))[lane + 64 * j] = w; } }
;         if (mod != cur_mod) { cur_mod = mod; const float* shp = mods_l + mod * 6144 + sh_off; const float* scp = mods_l + mod * 6144 + sc_off;
; #pragma unroll
;             for (int j = 0; j < 4; ++j) { gs[j] = ((const f32x4*)gam)[lane + 64 * j] * (((const f32x4*)scp)[lane + 64 * j] + 1.0f); shv[j] = ((const f32x4*)shp)[lane + 64 * j]; } }
;         if (isc && npart > 0) {
;             for (int ks = 0; ks < npart; ++ks) { const f32x4* pp = (const f32x4*)(part + ((size_t)ks * MC + (row - ML)) * DM);
; #pragma unroll
;                 for (int j = 0; j < 4; ++j) v[j] += pp[lane + 64 * j]; }
; #pragma unroll
;             for (int j = 0; j < 4; ++j) ((f32x4*)(srcC + (size_t)(row - ML) * DM))[lane + 64 * j] = v[j];
;         }
;         float s = 0.f;
; #pragma unroll
;         for (int j = 0; j < 4; ++j) s += (v[j].x * v[j].x + v[j].y * v[j].y) + (v[j].z * v[j].z + v[j].w * v[j].w);
;         s = wave_sum(s, lane); const float rstd = 1.0f / sqrtf(s * (1.0f / DM) + 1e-6f);
; #pragma unroll
;         for (int j = 0; j < 4; ++j) { const f32x4 y = v[j] * rstd * gs[j] + shv[j]; u32x2 w; w.x = pk2(y.x, y.y); w.y = pk2(y.z, y.w);
;             ((u32x2*)(H + (size_t)row * DM))[lane + 64 * j] = w; }
.Ln7_modokB:
	global_load_dwordx4 v[108:111], v86, s[34:35]
	global_load_dwordx4 v[112:115], v86, s[34:35] offset:1024
	s_add_i32 s11, s46, s12
	s_cmp_lt_i32 s11, 0x8000
	s_cselect_b32 s46, s11, s46
	s_cselect_b32 s11, s13, 0
	s_add_u32 s34, s34, s11
	s_addc_u32 s35, s35, 0
	v_pk_mul_f32 v[90:91], v[56:57], v[56:57]
	v_pk_mul_f32 v[92:93], v[54:55], v[54:55]
	v_pk_mul_f32 v[4:5], v[60:61], v[60:61]
	v_pk_mul_f32 v[88:89], v[58:59], v[58:59]
	v_pk_mov_b32 v[94:95], v[92:93], v[90:91] op_sel:[1,0]
	v_mov_b32_e32 v93, v91
	v_pk_add_f32 v[90:91], v[94:95], v[92:93]
	v_pk_mov_b32 v[92:93], v[88:89], v[4:5] op_sel:[1,0]
	v_mov_b32_e32 v89, v5
	v_pk_add_f32 v[4:5], v[92:93], v[88:89]
	v_pk_add_f32 v[90:91], v[90:91], v[90:91] op_sel_hi:[0,1]
	v_pk_add_f32 v[4:5], v[4:5], v[4:5] op_sel_hi:[0,1]
	v_mul_f32_e32 v4, v62, v62
	v_pk_fma_f32 v[88:89], v[62:63], v[62:63], v[4:5] op_sel_hi:[1,1,0]
	v_mul_f32_e32 v4, v64, v64
	v_pk_fma_f32 v[92:93], v[64:65], v[64:65], v[4:5] op_sel_hi:[1,1,0]
	v_mul_f32_e32 v88, v66, v66
	v_mul_f32_e32 v92, v67, v67
	v_mul_f32_e32 v90, v68, v68
	v_mul_f32_e32 v4, v69, v69
	v_pk_add_f32 v[88:89], v[88:89], v[92:93]
	v_pk_add_f32 v[4:5], v[90:91], v[4:5]
	v_pk_add_f32 v[4:5], v[88:89], v[4:5]
	s_nop 0
	v_add_f32_e32 v3, v4, v5
	ds_bpermute_b32 v4, v1, v3
	s_waitcnt lgkmcnt(0)
	v_add_f32_e32 v3, v3, v4
	ds_bpermute_b32 v4, v71, v3
	s_waitcnt lgkmcnt(0)
	v_add_f32_e32 v3, v3, v4
	ds_bpermute_b32 v4, v73, v3
	s_waitcnt lgkmcnt(0)
	v_add_f32_e32 v3, v3, v4
	ds_bpermute_b32 v4, v96, v3
	s_waitcnt lgkmcnt(0)
	v_add_f32_e32 v3, v3, v4
	ds_bpermute_b32 v4, v97, v3
	s_waitcnt lgkmcnt(0)
	v_add_f32_e32 v3, v3, v4
	ds_bpermute_b32 v4, v98, v3
	s_waitcnt lgkmcnt(0)
	v_add_f32_e32 v3, v3, v4
	v_fmamk_f32 v3, v3, 0x3a800000, v238
	v_mul_f32_e32 v4, 0x4f800000, v3
	v_cmp_gt_f32_e32 vcc, s58, v3
	s_nop 1
	v_cndmask_b32_e32 v3, v3, v4, vcc
	v_sqrt_f32_e32 v4, v3
	s_nop 0
	v_add_u32_e32 v5, -1, v4
	v_add_u32_e32 v75, 1, v4
	v_fma_f32 v88, -v5, v4, v3
	v_fma_f32 v89, -v75, v4, v3
	v_cmp_ge_f32_e64 s[4:5], 0, v88
	s_nop 1
	v_cndmask_b32_e64 v4, v4, v5, s[4:5]
	v_cmp_lt_f32_e64 s[4:5], 0, v89
	s_nop 1
	v_cndmask_b32_e64 v4, v4, v75, s[4:5]
	v_mul_f32_e32 v5, 0x37800000, v4
	v_cndmask_b32_e32 v4, v4, v5, vcc
	v_cmp_class_f32_e32 vcc, v3, v248
	s_nop 1
	v_cndmask_b32_e32 v3, v4, v3, vcc
	v_div_scale_f32 v75, s[4:5], v3, v3, 1.0
	v_rcp_f32_e32 v88, v75
	v_div_scale_f32 v89, vcc, 1.0, v3, 1.0
	v_fma_f32 v90, -v75, v88, 1.0
	v_fmac_f32_e32 v88, v90, v88
	v_mul_f32_e32 v90, v89, v88
	v_fma_f32 v91, -v75, v90, v89
	v_fmac_f32_e32 v90, v91, v88
	v_fma_f32 v75, -v75, v90, v89
	v_div_fmas_f32 v75, v75, v88, v90
	v_div_fixup_f32 v88, v75, v3, 1.0
	s_waitcnt vmcnt(2)
	v_pk_mul_f32 v[54:55], v[54:55], v[88:89] op_sel_hi:[1,0]
	v_pk_mul_f32 v[56:57], v[56:57], v[88:89] op_sel_hi:[1,0]
	v_pk_fma_f32 v[54:55], v[6:7], v[54:55], v[10:11]
	v_pk_fma_f32 v[56:57], v[8:9], v[56:57], v[12:13]
	v_cvt_pk_bf16_f32 v120, v54, v55
	v_cvt_pk_bf16_f32 v121, v56, v57
	v_pk_mul_f32 v[58:59], v[58:59], v[88:89] op_sel_hi:[1,0]
	v_pk_mul_f32 v[60:61], v[60:61], v[88:89] op_sel_hi:[1,0]
	v_pk_fma_f32 v[58:59], v[14:15], v[58:59], v[18:19]
	v_pk_fma_f32 v[60:61], v[16:17], v[60:61], v[20:21]
	v_cvt_pk_bf16_f32 v122, v58, v59
	v_cvt_pk_bf16_f32 v123, v60, v61
	global_store_dwordx4 v86, v[120:123], s[36:37]
	v_pk_mul_f32 v[62:63], v[62:63], v[88:89] op_sel_hi:[1,0]
	v_pk_mul_f32 v[64:65], v[64:65], v[88:89] op_sel_hi:[1,0]
	v_pk_fma_f32 v[62:63], v[26:27], v[62:63], v[30:31]
	v_pk_fma_f32 v[64:65], v[28:29], v[64:65], v[32:33]
	v_cvt_pk_bf16_f32 v124, v62, v63
	v_cvt_pk_bf16_f32 v125, v64, v65
	v_pk_mul_f32 v[66:67], v[66:67], v[88:89] op_sel_hi:[1,0]
	v_pk_mul_f32 v[68:69], v[68:69], v[88:89] op_sel_hi:[1,0]
	v_pk_fma_f32 v[66:67], v[38:39], v[66:67], v[46:47]
	v_pk_fma_f32 v[68:69], v[40:41], v[68:69], v[48:49]
	v_cvt_pk_bf16_f32 v126, v66, v67
	v_cvt_pk_bf16_f32 v127, v68, v69
	global_store_dwordx4 v86, v[124:127], s[36:37] offset:1024
	v_lshlrev_b32_e32 v54, 16, v100
	v_and_b32_e32 v55, 0xffff0000, v100
	v_lshlrev_b32_e32 v56, 16, v101
	v_and_b32_e32 v57, 0xffff0000, v101
	v_lshlrev_b32_e32 v58, 16, v102
	v_and_b32_e32 v59, 0xffff0000, v102
	v_lshlrev_b32_e32 v60, 16, v103
	v_and_b32_e32 v61, 0xffff0000, v103
	v_lshlrev_b32_e32 v62, 16, v104
	v_and_b32_e32 v63, 0xffff0000, v104
	v_lshlrev_b32_e32 v64, 16, v105
	v_and_b32_e32 v65, 0xffff0000, v105
	v_lshlrev_b32_e32 v66, 16, v106
	v_and_b32_e32 v67, 0xffff0000, v106
	v_lshlrev_b32_e32 v68, 16, v107
	v_and_b32_e32 v69, 0xffff0000, v107
	s_add_i32 s8, s8, s12
	s_add_u32 s36, s36, s13
	s_addc_u32 s37, s37, 0
	s_cmp_lt_i32 s8, 0x8000
	s_cbranch_scc0 .Ln7_ctx
	s_branch .Ln7_loopA

;     ...
;         if (mod != cur_mod) { cur_mod = mod; const float* shp = mods_l + mod * 6144 + sh_off; const float* scp = mods_l + mod * 6144 + sc_off;
; #pragma unroll
;             for (int j = 0; j < 4; ++j) { gs[j] = ((const f32x4*)gam)[lane + 64 * j] * (((const f32x4*)scp)[lane + 64 * j] + 1.0f); shv[j] = ((const f32x4*)shp)[lane + 64 * j]; } }
;         if (isc && npart > 0) {
;             for (int ks = 0; ks < npart; ++ks) { const f32x4* pp = (const f32x4*)(part + ((size_t)ks * MC + (row - ML)) * DM);
; #pragma unroll
;                 for (int j = 0; j < 4; ++j) v[j] += pp[lane + 64 * j]; }
; #pragma unroll
;             for (int j = 0; j < 4; ++j) ((f32x4*)(srcC + (size_t)(row - ML) * DM))[lane + 64 * j] = v[j];
.Ln7_ctxloop:
	s_add_u32 s54, s80, 0x36000
	s_addc_u32 s55, s81, 0
	s_add_u32 s42, s80, 0x37000
	s_addc_u32 s43, s81, 0
	global_load_dwordx4 v[10:13], v74, s[42:43]
	global_load_dwordx4 v[18:21], v74, s[42:43] offset:16
	global_load_dwordx4 v[30:33], v74, s[42:43] offset:2048
	global_load_dwordx4 v[46:49], v74, s[42:43] offset:2064
	global_load_dwordx4 v[6:9], v74, s[0:1]
	global_load_dwordx4 v[14:17], v74, s[0:1] offset:16
	global_load_dwordx4 v[26:29], v74, s[0:1] offset:2048
	global_load_dwordx4 v[38:41], v74, s[0:1] offset:2064
	s_add_i32 s6, s8, 0xffff8000
	s_mov_b32 s7, 0
	s_lshl_b64 s[6:7], s[6:7], 12
	s_add_u32 s84, s20, s6
	s_addc_u32 s85, s21, s7
	global_load_dwordx4 v[54:57], v74, s[84:85]
	global_load_dwordx4 v[58:61], v74, s[84:85] offset:16
	global_load_dwordx4 v[62:65], v74, s[84:85] offset:2048
	global_load_dwordx4 v[66:69], v74, s[84:85] offset:2064
	s_waitcnt vmcnt(0)
	v_pk_add_f32 v[10:11], v[10:11], 1.0 op_sel_hi:[1,0]
	v_pk_add_f32 v[12:13], v[12:13], 1.0 op_sel_hi:[1,0]
	v_pk_mul_f32 v[6:7], v[6:7], v[10:11]
	v_pk_mul_f32 v[8:9], v[8:9], v[12:13]
	v_pk_add_f32 v[18:19], v[18:19], 1.0 op_sel_hi:[1,0]
	v_pk_add_f32 v[20:21], v[20:21], 1.0 op_sel_hi:[1,0]
	v_pk_mul_f32 v[14:15], v[14:15], v[18:19]
	v_pk_mul_f32 v[16:17], v[16:17], v[20:21]
	v_pk_add_f32 v[30:31], v[30:31], 1.0 op_sel_hi:[1,0]
	v_pk_add_f32 v[32:33], v[32:33], 1.0 op_sel_hi:[1,0]
	v_pk_mul_f32 v[26:27], v[26:27], v[30:31]
	v_pk_mul_f32 v[28:29], v[28:29], v[32:33]
	v_pk_add_f32 v[46:47], v[46:47], 1.0 op_sel_hi:[1,0]
	v_pk_add_f32 v[48:49], v[48:49], 1.0 op_sel_hi:[1,0]
	v_pk_mul_f32 v[38:39], v[38:39], v[46:47]
	v_pk_mul_f32 v[40:41], v[40:41], v[48:49]
	global_load_dwordx4 v[10:13], v74, s[54:55]
	global_load_dwordx4 v[18:21], v74, s[54:55] offset:16
	global_load_dwordx4 v[30:33], v74, s[54:55] offset:2048
	global_load_dwordx4 v[46:49], v74, s[54:55] offset:2064
	s_add_u32 s86, s18, s6
	s_addc_u32 s87, s19, s7
	s_add_u32 s42, s86, 0x0
	s_addc_u32 s43, s87, 0
	global_load_dwordx4 v[116:119], v74, s[42:43]
	global_load_dwordx4 v[120:123], v74, s[42:43] offset:16
	global_load_dwordx4 v[124:127], v74, s[42:43] offset:2048
	global_load_dwordx4 v[128:131], v74, s[42:43] offset:2064
	s_add_u32 s42, s86, 0x400000
	s_addc_u32 s43, s87, 0
	global_load_dwordx4 v[132:135], v74, s[42:43]
	global_load_dwordx4 v[136:139], v74, s[42:43] offset:16
	global_load_dwordx4 v[140:143], v74, s[42:43] offset:2048
	global_load_dwordx4 v[144:147], v74, s[42:43] offset:2064
	s_add_u32 s42, s86, 0x800000
	s_addc_u32 s43, s87, 0
	global_load_dwordx4 v[148:151], v74, s[42:43]
	global_load_dwordx4 v[152:155], v74, s[42:43] offset:16
	global_load_dwordx4 v[156:159], v74, s[42:43] offset:2048
	global_load_dwordx4 v[160:163], v74, s[42:43] offset:2064
	s_add_u32 s42, s86, 0xc00000
	s_addc_u32 s43, s87, 0
	global_load_dwordx4 v[164:167], v74, s[42:43]
	global_load_dwordx4 v[168:171], v74, s[42:43] offset:16
	global_load_dwordx4 v[172:175], v74, s[42:43] offset:2048
	global_load_dwordx4 v[176:179], v74, s[42:43] offset:2064
	s_waitcnt vmcnt(0)
	v_pk_add_f32 v[54:55], v[54:55], v[116:117]
	v_pk_add_f32 v[56:57], v[56:57], v[118:119]
	v_pk_add_f32 v[58:59], v[58:59], v[120:121]
	v_pk_add_f32 v[60:61], v[60:61], v[122:123]
	v_pk_add_f32 v[62:63], v[62:63], v[124:125]
	v_pk_add_f32 v[64:65], v[64:65], v[126:127]
	v_pk_add_f32 v[66:67], v[66:67], v[128:129]
	v_pk_add_f32 v[68:69], v[68:69], v[130:131]
	v_pk_add_f32 v[54:55], v[54:55], v[132:133]
	v_pk_add_f32 v[56:57], v[56:57], v[134:135]
	v_pk_add_f32 v[58:59], v[58:59], v[136:137]
	v_pk_add_f32 v[60:61], v[60:61], v[138:139]
	v_pk_add_f32 v[62:63], v[62:63], v[140:141]
	v_pk_add_f32 v[64:65], v[64:65], v[142:143]
	v_pk_add_f32 v[66:67], v[66:67], v[144:145]
	v_pk_add_f32 v[68:69], v[68:69], v[146:147]
	v_pk_add_f32 v[54:55], v[54:55], v[148:149]
	v_pk_add_f32 v[56:57], v[56:57], v[150:151]
	v_pk_add_f32 v[58:59], v[58:59], v[152:153]
	v_pk_add_f32 v[60:61], v[60:61], v[154:155]
	v_pk_add_f32 v[62:63], v[62:63], v[156:157]
	v_pk_add_f32 v[64:65], v[64:65], v[158:159]
	v_pk_add_f32 v[66:67], v[66:67], v[160:161]
	v_pk_add_f32 v[68:69], v[68:69], v[162:163]
	v_pk_add_f32 v[54:55], v[54:55], v[164:165]
	v_pk_add_f32 v[56:57], v[56:57], v[166:167]
	v_pk_add_f32 v[58:59], v[58:59], v[168:169]
	v_pk_add_f32 v[60:61], v[60:61], v[170:171]
	v_pk_add_f32 v[62:63], v[62:63], v[172:173]
	v_pk_add_f32 v[64:65], v[64:65], v[174:175]
	v_pk_add_f32 v[66:67], v[66:67], v[176:177]
	v_pk_add_f32 v[68:69], v[68:69], v[178:179]
	s_add_u32 s42, s86, 0x1000000
	s_addc_u32 s43, s87, 0
	global_load_dwordx4 v[116:119], v74, s[42:43]
	global_load_dwordx4 v[120:123], v74, s[42:43] offset:16
	global_load_dwordx4 v[124:127], v74, s[42:43] offset:2048
	global_load_dwordx4 v[128:131], v74, s[42:43] offset:2064
	s_add_u32 s42, s86, 0x1400000
	s_addc_u32 s43, s87, 0
	global_load_dwordx4 v[132:135], v74, s[42:43]
	global_load_dwordx4 v[136:139], v74, s[42:43] offset:16
	global_load_dwordx4 v[140:143], v74, s[42:43] offset:2048
	global_load_dwordx4 v[144:147], v74, s[42:43] offset:2064
	s_add_u32 s42, s86, 0x1800000
	s_addc_u32 s43, s87, 0
	global_load_dwordx4 v[148:151], v74, s[42:43]
	global_load_dwordx4 v[152:155], v74, s[42:43] offset:16
	global_load_dwordx4 v[156:159], v74, s[42:43] offset:2048
	global_load_dwordx4 v[160:163], v74, s[42:43] offset:2064
	s_add_u32 s42, s86, 0x1c00000
	s_addc_u32 s43, s87, 0
	global_load_dwordx4 v[164:167], v74, s[42:43]
	global_load_dwordx4 v[168:171], v74, s[42:43] offset:16
	global_load_dwordx4 v[172:175], v74, s[42:43] offset:2048
	global_load_dwordx4 v[176:179], v74, s[42:43] offset:2064
	s_waitcnt vmcnt(0)
;     ...
;         if (isc && npart > 0) {
;             for (int ks = 0; ks < npart; ++ks) { const f32x4* pp = (const f32x4*)(part + ((size_t)ks * MC + (row - ML)) * DM);
; #pragma unroll
;                 for (int j = 0; j < 4; ++j) v[j] += pp[lane + 64 * j]; }
; #pragma unroll
;             for (int j = 0; j < 4; ++j) ((f32x4*)(srcC + (size_t)(row - ML) * DM))[lane + 64 * j] = v[j];
;         }
;         float s = 0.f;
; #pragma unroll
;         for (int j = 0; j < 4; ++j) s += (v[j].x * v[j].x + v[j].y * v[j].y) + (v[j].z * v[j].z + v[j].w * v[j].w);
	v_pk_add_f32 v[54:55], v[54:55], v[116:117]
	v_pk_add_f32 v[56:57], v[56:57], v[118:119]
	v_pk_add_f32 v[58:59], v[58:59], v[120:121]
	v_pk_add_f32 v[60:61], v[60:61], v[122:123]
	v_pk_add_f32 v[62:63], v[62:63], v[124:125]
	v_pk_add_f32 v[64:65], v[64:65], v[126:127]
	v_pk_add_f32 v[66:67], v[66:67], v[128:129]
	v_pk_add_f32 v[68:69], v[68:69], v[130:131]
	v_pk_add_f32 v[54:55], v[54:55], v[132:133]
	v_pk_add_f32 v[56:57], v[56:57], v[134:135]
	v_pk_add_f32 v[58:59], v[58:59], v[136:137]
	v_pk_add_f32 v[60:61], v[60:61], v[138:139]
	v_pk_add_f32 v[62:63], v[62:63], v[140:141]
	v_pk_add_f32 v[64:65], v[64:65], v[142:143]
	v_pk_add_f32 v[66:67], v[66:67], v[144:145]
	v_pk_add_f32 v[68:69], v[68:69], v[146:147]
	v_pk_add_f32 v[54:55], v[54:55], v[148:149]
	v_pk_add_f32 v[56:57], v[56:57], v[150:151]
	v_pk_add_f32 v[58:59], v[58:59], v[152:153]
	v_pk_add_f32 v[60:61], v[60:61], v[154:155]
	v_pk_add_f32 v[62:63], v[62:63], v[156:157]
	v_pk_add_f32 v[64:65], v[64:65], v[158:159]
	v_pk_add_f32 v[66:67], v[66:67], v[160:161]
	v_pk_add_f32 v[68:69], v[68:69], v[162:163]
	v_pk_add_f32 v[54:55], v[54:55], v[164:165]
	v_pk_add_f32 v[56:57], v[56:57], v[166:167]
	v_pk_add_f32 v[58:59], v[58:59], v[168:169]
	v_pk_add_f32 v[60:61], v[60:61], v[170:171]
	v_pk_add_f32 v[62:63], v[62:63], v[172:173]
	v_pk_add_f32 v[64:65], v[64:65], v[174:175]
	v_pk_add_f32 v[66:67], v[66:67], v[176:177]
	v_pk_add_f32 v[68:69], v[68:69], v[178:179]
	s_add_u32 s42, s86, 0x2000000
	s_addc_u32 s43, s87, 0
	global_load_dwordx4 v[116:119], v74, s[42:43]
	global_load_dwordx4 v[120:123], v74, s[42:43] offset:16
	global_load_dwordx4 v[124:127], v74, s[42:43] offset:2048
	global_load_dwordx4 v[128:131], v74, s[42:43] offset:2064
	s_add_u32 s42, s86, 0x2400000
	s_addc_u32 s43, s87, 0
	global_load_dwordx4 v[132:135], v74, s[42:43]
	global_load_dwordx4 v[136:139], v74, s[42:43] offset:16
	global_load_dwordx4 v[140:143], v74, s[42:43] offset:2048
	global_load_dwordx4 v[144:147], v74, s[42:43] offset:2064
	s_add_u32 s42, s86, 0x2800000
	s_addc_u32 s43, s87, 0
	global_load_dwordx4 v[148:151], v74, s[42:43]
	global_load_dwordx4 v[152:155], v74, s[42:43] offset:16
	global_load_dwordx4 v[156:159], v74, s[42:43] offset:2048
	global_load_dwordx4 v[160:163], v74, s[42:43] offset:2064
	s_waitcnt vmcnt(0)
	v_pk_add_f32 v[54:55], v[54:55], v[116:117]
	v_pk_add_f32 v[56:57], v[56:57], v[118:119]
	v_pk_add_f32 v[58:59], v[58:59], v[120:121]
	v_pk_add_f32 v[60:61], v[60:61], v[122:123]
	v_pk_add_f32 v[62:63], v[62:63], v[124:125]
	v_pk_add_f32 v[64:65], v[64:65], v[126:127]
	v_pk_add_f32 v[66:67], v[66:67], v[128:129]
	v_pk_add_f32 v[68:69], v[68:69], v[130:131]
	v_pk_add_f32 v[54:55], v[54:55], v[132:133]
	v_pk_add_f32 v[56:57], v[56:57], v[134:135]
	v_pk_add_f32 v[58:59], v[58:59], v[136:137]
	v_pk_add_f32 v[60:61], v[60:61], v[138:139]
	v_pk_add_f32 v[62:63], v[62:63], v[140:141]
	v_pk_add_f32 v[64:65], v[64:65], v[142:143]
	v_pk_add_f32 v[66:67], v[66:67], v[144:145]
	v_pk_add_f32 v[68:69], v[68:69], v[146:147]
	v_pk_add_f32 v[54:55], v[54:55], v[148:149]
	v_pk_add_f32 v[56:57], v[56:57], v[150:151]
	v_pk_add_f32 v[58:59], v[58:59], v[152:153]
	v_pk_add_f32 v[60:61], v[60:61], v[154:155]
	v_pk_add_f32 v[62:63], v[62:63], v[156:157]
	v_pk_add_f32 v[64:65], v[64:65], v[158:159]
	v_pk_add_f32 v[66:67], v[66:67], v[160:161]
	v_pk_add_f32 v[68:69], v[68:69], v[162:163]
	global_store_dwordx4 v74, v[54:57], s[84:85]
	global_store_dwordx4 v74, v[58:61], s[84:85] offset:16
	global_store_dwordx4 v74, v[62:65], s[84:85] offset:2048
	global_store_dwordx4 v74, v[66:69], s[84:85] offset:2064
	s_ashr_i32 s11, s8, 31
	s_mov_b32 s6, s8
	s_mov_b32 s7, s11
	s_lshl_b64 s[6:7], s[6:7], 11
	s_add_u32 s36, s75, s6
	s_addc_u32 s37, s76, s7
	v_pk_mul_f32 v[90:91], v[56:57], v[56:57]
	v_pk_mul_f32 v[92:93], v[54:55], v[54:55]
	v_pk_mul_f32 v[4:5], v[60:61], v[60:61]
	v_pk_mul_f32 v[88:89], v[58:59], v[58:59]
	v_pk_mov_b32 v[94:95], v[92:93], v[90:91] op_sel:[1,0]
	v_mov_b32_e32 v93, v91
	v_pk_add_f32 v[90:91], v[94:95], v[92:93]
	v_pk_mov_b32 v[92:93], v[88:89], v[4:5] op_sel:[1,0]
	v_mov_b32_e32 v89, v5
	v_pk_add_f32 v[4:5], v[92:93], v[88:89]
	v_pk_add_f32 v[90:91], v[90:91], v[90:91] op_sel_hi:[0,1]
	v_pk_add_f32 v[4:5], v[4:5], v[4:5] op_sel_hi:[0,1]
	v_mul_f32_e32 v4, v62, v62
	v_pk_fma_f32 v[88:89], v[62:63], v[62:63], v[4:5] op_sel_hi:[1,1,0]
	v_mul_f32_e32 v4, v64, v64
	v_pk_fma_f32 v[92:93], v[64:65], v[64:65], v[4:5] op_sel_hi:[1,1,0]
	v_mul_f32_e32 v88, v66, v66
	v_mul_f32_e32 v92, v67, v67
	v_mul_f32_e32 v90, v68, v68
	v_mul_f32_e32 v4, v69, v69
	v_pk_add_f32 v[88:89], v[88:89], v[92:93]
	v_pk_add_f32 v[4:5], v[90:91], v[4:5]
	v_pk_add_f32 v[4:5], v[88:89], v[4:5]
	s_nop 0
	v_add_f32_e32 v3, v4, v5
	ds_bpermute_b32 v4, v1, v3
	s_waitcnt lgkmcnt(0)
; __device__ __forceinline__ unsigned pk2(float lo, float hi) { const f32x2_t v = {lo, hi}; return __builtin_bit_cast(unsigned, __builtin_convertvector(v, bf16x2_t)); }
; __device__ __forceinline__ float lane_xor(float v, int lane, int o) { return __int_as_float(__builtin_amdgcn_ds_bpermute((lane ^ o) << 2, __float_as_int(v))); }
; __device__ __forceinline__ float wave_sum(float v, int lane) {
; #pragma unroll
;     for (int o = 1; o < 64; o <<= 1) v += lane_xor(v, lane, o);
;     return v;
;     ...
;         float s = 0.f;
; #pragma unroll
;         for (int j = 0; j < 4; ++j) s += (v[j].x * v[j].x + v[j].y * v[j].y) + (v[j].z * v[j].z + v[j].w * v[j].w);
;         s = wave_sum(s, lane); const float rstd = 1.0f / sqrtf(s * (1.0f / DM) + 1e-6f);
; #pragma unroll
;         for (int j = 0; j < 4; ++j) { const f32x4 y = v[j] * rstd * gs[j] + shv[j]; u32x2 w; w.x = pk2(y.x, y.y); w.y = pk2(y.z, y.w);
;             ((u32x2*)(H + (size_t)row * DM))[lane + 64 * j] = w; }
	v_add_f32_e32 v3, v3, v4
	ds_bpermute_b32 v4, v71, v3
	s_waitcnt lgkmcnt(0)
	v_add_f32_e32 v3, v3, v4
	ds_bpermute_b32 v4, v73, v3
	s_waitcnt lgkmcnt(0)
	v_add_f32_e32 v3, v3, v4
	ds_bpermute_b32 v4, v96, v3
	s_waitcnt lgkmcnt(0)
	v_add_f32_e32 v3, v3, v4
	ds_bpermute_b32 v4, v97, v3
	s_waitcnt lgkmcnt(0)
	v_add_f32_e32 v3, v3, v4
	ds_bpermute_b32 v4, v98, v3
	s_waitcnt lgkmcnt(0)
	v_add_f32_e32 v3, v3, v4
	v_fmamk_f32 v3, v3, 0x3a800000, v238
	v_mul_f32_e32 v4, 0x4f800000, v3
	v_cmp_gt_f32_e32 vcc, s58, v3
	s_nop 1
	v_cndmask_b32_e32 v3, v3, v4, vcc
	v_sqrt_f32_e32 v4, v3
	s_nop 0
	v_add_u32_e32 v5, -1, v4
	v_add_u32_e32 v75, 1, v4
	v_fma_f32 v88, -v5, v4, v3
	v_fma_f32 v89, -v75, v4, v3
	v_cmp_ge_f32_e64 s[4:5], 0, v88
	s_nop 1
	v_cndmask_b32_e64 v4, v4, v5, s[4:5]
	v_cmp_lt_f32_e64 s[4:5], 0, v89
	s_nop 1
	v_cndmask_b32_e64 v4, v4, v75, s[4:5]
	v_mul_f32_e32 v5, 0x37800000, v4
	v_cndmask_b32_e32 v4, v4, v5, vcc
	v_cmp_class_f32_e32 vcc, v3, v248
	s_nop 1
	v_cndmask_b32_e32 v3, v4, v3, vcc
	v_div_scale_f32 v75, s[4:5], v3, v3, 1.0
	v_rcp_f32_e32 v88, v75
	v_div_scale_f32 v89, vcc, 1.0, v3, 1.0
	v_fma_f32 v90, -v75, v88, 1.0
	v_fmac_f32_e32 v88, v90, v88
	v_mul_f32_e32 v90, v89, v88
	v_fma_f32 v91, -v75, v90, v89
	v_fmac_f32_e32 v90, v91, v88
	v_fma_f32 v75, -v75, v90, v89
	v_div_fmas_f32 v75, v75, v88, v90
	v_div_fixup_f32 v88, v75, v3, 1.0
	v_pk_mul_f32 v[54:55], v[54:55], v[88:89] op_sel_hi:[1,0]
	v_pk_mul_f32 v[56:57], v[56:57], v[88:89] op_sel_hi:[1,0]
	v_pk_fma_f32 v[54:55], v[6:7], v[54:55], v[10:11]
	v_pk_fma_f32 v[56:57], v[8:9], v[56:57], v[12:13]
	v_cvt_pk_bf16_f32 v120, v54, v55
	v_cvt_pk_bf16_f32 v121, v56, v57
	v_pk_mul_f32 v[58:59], v[58:59], v[88:89] op_sel_hi:[1,0]
	v_pk_mul_f32 v[60:61], v[60:61], v[88:89] op_sel_hi:[1,0]
	v_pk_fma_f32 v[58:59], v[14:15], v[58:59], v[18:19]
	v_pk_fma_f32 v[60:61], v[16:17], v[60:61], v[20:21]
	v_cvt_pk_bf16_f32 v122, v58, v59
	v_cvt_pk_bf16_f32 v123, v60, v61
	global_store_dwordx4 v86, v[120:123], s[36:37]
	v_pk_mul_f32 v[62:63], v[62:63], v[88:89] op_sel_hi:[1,0]
	v_pk_mul_f32 v[64:65], v[64:65], v[88:89] op_sel_hi:[1,0]
	v_pk_fma_f32 v[62:63], v[26:27], v[62:63], v[30:31]
	v_pk_fma_f32 v[64:65], v[28:29], v[64:65], v[32:33]
	v_cvt_pk_bf16_f32 v124, v62, v63
	v_cvt_pk_bf16_f32 v125, v64, v65
	v_pk_mul_f32 v[66:67], v[66:67], v[88:89] op_sel_hi:[1,0]
	v_pk_mul_f32 v[68:69], v[68:69], v[88:89] op_sel_hi:[1,0]
	v_pk_fma_f32 v[66:67], v[38:39], v[66:67], v[46:47]
	v_pk_fma_f32 v[68:69], v[40:41], v[68:69], v[48:49]
	v_cvt_pk_bf16_f32 v126, v66, v67
	v_cvt_pk_bf16_f32 v127, v68, v69
	global_store_dwordx4 v86, v[124:127], s[36:37] offset:1024
	s_add_i32 s8, s8, s12
	s_cmp_lt_i32 s8, 0x8400
	s_cbranch_scc1 .Ln7_ctxloop

; __global__ void __launch_bounds__(NTHR, 2) mk_fwd(Args a) {
;     ...
;                     for (int row = gw; row < ML; row += NGW) {
;                         f32x4* xr = (f32x4*)(xres + (size_t)row * DM); f32x4 v[4]; float s = 0.f;
; #pragma unroll
;                         for (int j = 0; j < 4; ++j) { v[j] = ld_row4(nullptr, XB, nullptr, row, lane + 64 * j); s += (v[j].x * v[j].x + v[j].y * v[j].y) + (v[j].z * v[j].z + v[j].w * v[j].w); }
;                         s = wave_sum(s, lane); const float rstd = 1.0f / sqrtf(s * (1.0f / DM) + 1e-6f);
; #pragma unroll
;                         for (int j = 0; j < 4; ++j) xr[lane + 64 * j] = v[j] * rstd * ((const f32x4*)final_g)[lane + 64 * j];
;                     }
.Lnf_begin:
	s_cmp_lt_i32 s10, 0x8000
	s_cbranch_scc0 .Lnf_done
	v_lshlrev_b32_e32 v86, 4, v249
	v_lshlrev_b32_e32 v74, 5, v249
	v_lshlrev_b32_e32 v3, 2, v249
	v_xor_b32_e32 v1, 4, v3
	v_xor_b32_e32 v71, 8, v3
	v_xor_b32_e32 v73, 16, v3
	v_xor_b32_e32 v96, 32, v3
	v_xor_b32_e32 v97, 64, v3
	v_xor_b32_e32 v98, 0x80, v3
	s_load_dwordx4 s[84:87], s[28:29], 0x88
	s_mov_b32 s8, s10
	s_lshl_b32 s13, s12, 11
	s_lshl_b32 s3, s12, 12
	s_ashr_i32 s11, s10, 31
	s_lshl_b64 s[6:7], s[10:11], 11
	s_add_u32 s34, s30, s6
	s_addc_u32 s35, s31, s7
	s_lshl_b64 s[6:7], s[10:11], 12
	s_waitcnt lgkmcnt(0)
	s_add_u32 s36, s86, s6
	s_addc_u32 s37, s87, s7
	s_mov_b32 s46, s10
	global_load_dwordx4 v[6:9], v74, s[84:85]
	global_load_dwordx4 v[14:17], v74, s[84:85] offset:16
	global_load_dwordx4 v[26:29], v74, s[84:85] offset:2048
	global_load_dwordx4 v[38:41], v74, s[84:85] offset:2064
	global_load_dwordx4 v[100:103], v86, s[34:35]
	global_load_dwordx4 v[104:107], v86, s[34:35] offset:1024
	s_add_i32 s11, s46, s12
	s_cmp_lt_i32 s11, 0x8000
	s_cselect_b32 s46, s11, s46
	s_cselect_b32 s11, s13, 0
	s_add_u32 s34, s34, s11
	s_addc_u32 s35, s35, 0
	global_load_dwordx4 v[108:111], v86, s[34:35]
	global_load_dwordx4 v[112:115], v86, s[34:35] offset:1024
	s_add_i32 s11, s46, s12
	s_cmp_lt_i32 s11, 0x8000
	s_cselect_b32 s46, s11, s46
	s_cselect_b32 s11, s13, 0
	s_add_u32 s34, s34, s11
	s_addc_u32 s35, s35, 0
	s_waitcnt vmcnt(2)
	v_lshlrev_b32_e32 v54, 16, v100
	v_and_b32_e32 v55, 0xffff0000, v100
	v_lshlrev_b32_e32 v56, 16, v101
	v_and_b32_e32 v57, 0xffff0000, v101
	v_lshlrev_b32_e32 v58, 16, v102
	v_and_b32_e32 v59, 0xffff0000, v102
	v_lshlrev_b32_e32 v60, 16, v103
	v_and_b32_e32 v61, 0xffff0000, v103
	v_lshlrev_b32_e32 v62, 16, v104
	v_and_b32_e32 v63, 0xffff0000, v104
	v_lshlrev_b32_e32 v64, 16, v105
	v_and_b32_e32 v65, 0xffff0000, v105
	v_lshlrev_b32_e32 v66, 16, v106
	v_and_b32_e32 v67, 0xffff0000, v106
	v_lshlrev_b32_e32 v68, 16, v107
	v_and_b32_e32 v69, 0xffff0000, v107
.Lnf_loopA:
	global_load_dwordx4 v[100:103], v86, s[34:35]
	global_load_dwordx4 v[104:107], v86, s[34:35] offset:1024
	s_add_i32 s11, s46, s12
	s_cmp_lt_i32 s11, 0x8000
	s_cselect_b32 s46, s11, s46
	s_cselect_b32 s11, s13, 0
	s_add_u32 s34, s34, s11
	s_addc_u32 s35, s35, 0
	v_pk_mul_f32 v[90:91], v[56:57], v[56:57]
	v_pk_mul_f32 v[92:93], v[54:55], v[54:55]
	v_pk_mul_f32 v[4:5], v[60:61], v[60:61]
	v_pk_mul_f32 v[88:89], v[58:59], v[58:59]
	v_pk_mov_b32 v[94:95], v[92:93], v[90:91] op_sel:[1,0]
	v_mov_b32_e32 v93, v91
	v_pk_add_f32 v[90:91], v[94:95], v[92:93]
	v_pk_mov_b32 v[92:93], v[88:89], v[4:5] op_sel:[1,0]
	v_mov_b32_e32 v89, v5
	v_pk_add_f32 v[4:5], v[92:93], v[88:89]
	v_pk_add_f32 v[90:91], v[90:91], v[90:91] op_sel_hi:[0,1]
	v_pk_add_f32 v[4:5], v[4:5], v[4:5] op_sel_hi:[0,1]
	v_mul_f32_e32 v4, v62, v62
	v_pk_fma_f32 v[88:89], v[62:63], v[62:63], v[4:5] op_sel_hi:[1,1,0]
	v_mul_f32_e32 v4, v64, v64
	v_pk_fma_f32 v[92:93], v[64:65], v[64:65], v[4:5] op_sel_hi:[1,1,0]
	v_mul_f32_e32 v88, v66, v66
	v_mul_f32_e32 v92, v67, v67
	v_mul_f32_e32 v90, v68, v68
	v_mul_f32_e32 v4, v69, v69
	v_pk_add_f32 v[88:89], v[88:89], v[92:93]
	v_pk_add_f32 v[4:5], v[90:91], v[4:5]
	v_pk_add_f32 v[4:5], v[88:89], v[4:5]
	s_nop 0
	v_add_f32_e32 v3, v4, v5
	ds_bpermute_b32 v4, v1, v3
	s_waitcnt lgkmcnt(0)
	v_add_f32_e32 v3, v3, v4
	ds_bpermute_b32 v4, v71, v3
	s_waitcnt lgkmcnt(0)
	v_add_f32_e32 v3, v3, v4
	ds_bpermute_b32 v4, v73, v3
	s_waitcnt lgkmcnt(0)
	v_add_f32_e32 v3, v3, v4
	ds_bpermute_b32 v4, v96, v3
	s_waitcnt lgkmcnt(0)
	v_add_f32_e32 v3, v3, v4
	ds_bpermute_b32 v4, v97, v3
	s_waitcnt lgkmcnt(0)
	v_add_f32_e32 v3, v3, v4
	ds_bpermute_b32 v4, v98, v3
	s_waitcnt lgkmcnt(0)
	v_add_f32_e32 v3, v3, v4
	v_fmamk_f32 v3, v3, 0x3a800000, v238
	v_mul_f32_e32 v4, 0x4f800000, v3
	v_cmp_gt_f32_e32 vcc, s58, v3
	s_nop 1
	v_cndmask_b32_e32 v3, v3, v4, vcc
	v_sqrt_f32_e32 v4, v3
	s_nop 0
	v_add_u32_e32 v5, -1, v4
	v_add_u32_e32 v75, 1, v4
	v_fma_f32 v88, -v5, v4, v3
	v_fma_f32 v89, -v75, v4, v3
	v_cmp_ge_f32_e64 s[4:5], 0, v88
	s_nop 1
	v_cndmask_b32_e64 v4, v4, v5, s[4:5]
	v_cmp_lt_f32_e64 s[4:5], 0, v89
	s_nop 1
	v_cndmask_b32_e64 v4, v4, v75, s[4:5]
	v_mul_f32_e32 v5, 0x37800000, v4
	v_cndmask_b32_e32 v4, v4, v5, vcc
	v_cmp_class_f32_e32 vcc, v3, v248
	s_nop 1
	v_cndmask_b32_e32 v3, v4, v3, vcc
	v_div_scale_f32 v75, s[4:5], v3, v3, 1.0
	v_rcp_f32_e32 v88, v75
	v_div_scale_f32 v89, vcc, 1.0, v3, 1.0
	v_fma_f32 v90, -v75, v88, 1.0
	v_fmac_f32_e32 v88, v90, v88
	v_mul_f32_e32 v90, v89, v88
	v_fma_f32 v91, -v75, v90, v89
	v_fmac_f32_e32 v90, v91, v88
	v_fma_f32 v75, -v75, v90, v89
	v_div_fmas_f32 v75, v75, v88, v90
	v_div_fixup_f32 v88, v75, v3, 1.0
	s_waitcnt vmcnt(2)
	v_pk_mul_f32 v[54:55], v[54:55], v[88:89] op_sel_hi:[1,0]
	v_pk_mul_f32 v[56:57], v[56:57], v[88:89] op_sel_hi:[1,0]
	v_pk_mul_f32 v[54:55], v[54:55], v[6:7]
	v_pk_mul_f32 v[56:57], v[56:57], v[8:9]
	global_store_dwordx4 v74, v[54:57], s[36:37]
	v_pk_mul_f32 v[58:59], v[58:59], v[88:89] op_sel_hi:[1,0]
	v_pk_mul_f32 v[60:61], v[60:61], v[88:89] op_sel_hi:[1,0]
	v_pk_mul_f32 v[58:59], v[58:59], v[14:15]
	v_pk_mul_f32 v[60:61], v[60:61], v[16:17]
	global_store_dwordx4 v74, v[58:61], s[36:37] offset:16
	v_pk_mul_f32 v[62:63], v[62:63], v[88:89] op_sel_hi:[1,0]
	v_pk_mul_f32 v[64:65], v[64:65], v[88:89] op_sel_hi:[1,0]
	v_pk_mul_f32 v[62:63], v[62:63], v[26:27]
	v_pk_mul_f32 v[64:65], v[64:65], v[28:29]
	global_store_dwordx4 v74, v[62:65], s[36:37] offset:2048
	v_pk_mul_f32 v[66:67], v[66:67], v[88:89] op_sel_hi:[1,0]
	v_pk_mul_f32 v[68:69], v[68:69], v[88:89] op_sel_hi:[1,0]
	v_pk_mul_f32 v[66:67], v[66:67], v[38:39]
	v_pk_mul_f32 v[68:69], v[68:69], v[40:41]
	global_store_dwordx4 v74, v[66:69], s[36:37] offset:2064
	s_nop 1
	v_lshlrev_b32_e32 v54, 16, v108
	v_and_b32_e32 v55, 0xffff0000, v108
	v_lshlrev_b32_e32 v56, 16, v109
	v_and_b32_e32 v57, 0xffff0000, v109
	v_lshlrev_b32_e32 v58, 16, v110
	v_and_b32_e32 v59, 0xffff0000, v110
	v_lshlrev_b32_e32 v60, 16, v111
	v_and_b32_e32 v61, 0xffff0000, v111
	v_lshlrev_b32_e32 v62, 16, v112
	v_and_b32_e32 v63, 0xffff0000, v112
	v_lshlrev_b32_e32 v64, 16, v113
	v_and_b32_e32 v65, 0xffff0000, v113
	v_lshlrev_b32_e32 v66, 16, v114
	v_and_b32_e32 v67, 0xffff0000, v114
	v_lshlrev_b32_e32 v68, 16, v115
	v_and_b32_e32 v69, 0xffff0000, v115
	s_add_i32 s8, s8, s12
	s_add_u32 s36, s36, s3
	s_addc_u32 s37, s37, 0
	s_cmp_lt_i32 s8, 0x8000
	s_cbranch_scc0 .Lnf_done
; __global__ void __launch_bounds__(NTHR, 2) mk_fwd(Args a) {
;     ...
;                     for (int row = gw; row < ML; row += NGW) {
;                         f32x4* xr = (f32x4*)(xres + (size_t)row * DM); f32x4 v[4]; float s = 0.f;
; #pragma unroll
;                         for (int j = 0; j < 4; ++j) { v[j] = ld_row4(nullptr, XB, nullptr, row, lane + 64 * j); s += (v[j].x * v[j].x + v[j].y * v[j].y) + (v[j].z * v[j].z + v[j].w * v[j].w); }
;                         s = wave_sum(s, lane); const float rstd = 1.0f / sqrtf(s * (1.0f / DM) + 1e-6f);
; #pragma unroll
;                         for (int j = 0; j < 4; ++j) xr[lane + 64 * j] = v[j] * rstd * ((const f32x4*)final_g)[lane + 64 * j];
;                     }
.Lnf_loopB:
	global_load_dwordx4 v[108:111], v86, s[34:35]
	global_load_dwordx4 v[112:115], v86, s[34:35] offset:1024
	s_add_i32 s11, s46, s12
	s_cmp_lt_i32 s11, 0x8000
	s_cselect_b32 s46, s11, s46
	s_cselect_b32 s11, s13, 0
	s_add_u32 s34, s34, s11
	s_addc_u32 s35, s35, 0
	v_pk_mul_f32 v[90:91], v[56:57], v[56:57]
	v_pk_mul_f32 v[92:93], v[54:55], v[54:55]
	v_pk_mul_f32 v[4:5], v[60:61], v[60:61]
	v_pk_mul_f32 v[88:89], v[58:59], v[58:59]
	v_pk_mov_b32 v[94:95], v[92:93], v[90:91] op_sel:[1,0]
	v_mov_b32_e32 v93, v91
	v_pk_add_f32 v[90:91], v[94:95], v[92:93]
	v_pk_mov_b32 v[92:93], v[88:89], v[4:5] op_sel:[1,0]
	v_mov_b32_e32 v89, v5
	v_pk_add_f32 v[4:5], v[92:93], v[88:89]
	v_pk_add_f32 v[90:91], v[90:91], v[90:91] op_sel_hi:[0,1]
	v_pk_add_f32 v[4:5], v[4:5], v[4:5] op_sel_hi:[0,1]
	v_mul_f32_e32 v4, v62, v62
	v_pk_fma_f32 v[88:89], v[62:63], v[62:63], v[4:5] op_sel_hi:[1,1,0]
	v_mul_f32_e32 v4, v64, v64
	v_pk_fma_f32 v[92:93], v[64:65], v[64:65], v[4:5] op_sel_hi:[1,1,0]
	v_mul_f32_e32 v88, v66, v66
	v_mul_f32_e32 v92, v67, v67
	v_mul_f32_e32 v90, v68, v68
	v_mul_f32_e32 v4, v69, v69
	v_pk_add_f32 v[88:89], v[88:89], v[92:93]
	v_pk_add_f32 v[4:5], v[90:91], v[4:5]
	v_pk_add_f32 v[4:5], v[88:89], v[4:5]
	s_nop 0
	v_add_f32_e32 v3, v4, v5
	ds_bpermute_b32 v4, v1, v3
	s_waitcnt lgkmcnt(0)
	v_add_f32_e32 v3, v3, v4
	ds_bpermute_b32 v4, v71, v3
	s_waitcnt lgkmcnt(0)
	v_add_f32_e32 v3, v3, v4
	ds_bpermute_b32 v4, v73, v3
	s_waitcnt lgkmcnt(0)
	v_add_f32_e32 v3, v3, v4
	ds_bpermute_b32 v4, v96, v3
	s_waitcnt lgkmcnt(0)
	v_add_f32_e32 v3, v3, v4
	ds_bpermute_b32 v4, v97, v3
	s_waitcnt lgkmcnt(0)
	v_add_f32_e32 v3, v3, v4
	ds_bpermute_b32 v4, v98, v3
	s_waitcnt lgkmcnt(0)
	v_add_f32_e32 v3, v3, v4
	v_fmamk_f32 v3, v3, 0x3a800000, v238
	v_mul_f32_e32 v4, 0x4f800000, v3
	v_cmp_gt_f32_e32 vcc, s58, v3
	s_nop 1
	v_cndmask_b32_e32 v3, v3, v4, vcc
	v_sqrt_f32_e32 v4, v3
	s_nop 0
	v_add_u32_e32 v5, -1, v4
	v_add_u32_e32 v75, 1, v4
	v_fma_f32 v88, -v5, v4, v3
	v_fma_f32 v89, -v75, v4, v3
	v_cmp_ge_f32_e64 s[4:5], 0, v88
	s_nop 1
	v_cndmask_b32_e64 v4, v4, v5, s[4:5]
	v_cmp_lt_f32_e64 s[4:5], 0, v89
	s_nop 1
	v_cndmask_b32_e64 v4, v4, v75, s[4:5]
	v_mul_f32_e32 v5, 0x37800000, v4
	v_cndmask_b32_e32 v4, v4, v5, vcc
	v_cmp_class_f32_e32 vcc, v3, v248
	s_nop 1
	v_cndmask_b32_e32 v3, v4, v3, vcc
	v_div_scale_f32 v75, s[4:5], v3, v3, 1.0
	v_rcp_f32_e32 v88, v75
	v_div_scale_f32 v89, vcc, 1.0, v3, 1.0
	v_fma_f32 v90, -v75, v88, 1.0
	v_fmac_f32_e32 v88, v90, v88
	v_mul_f32_e32 v90, v89, v88
	v_fma_f32 v91, -v75, v90, v89
	v_fmac_f32_e32 v90, v91, v88
	v_fma_f32 v75, -v75, v90, v89
	v_div_fmas_f32 v75, v75, v88, v90
	v_div_fixup_f32 v88, v75, v3, 1.0
	s_waitcnt vmcnt(2)
	v_pk_mul_f32 v[54:55], v[54:55], v[88:89] op_sel_hi:[1,0]
	v_pk_mul_f32 v[56:57], v[56:57], v[88:89] op_sel_hi:[1,0]
	v_pk_mul_f32 v[54:55], v[54:55], v[6:7]
	v_pk_mul_f32 v[56:57], v[56:57], v[8:9]
	global_store_dwordx4 v74, v[54:57], s[36:37]
	v_pk_mul_f32 v[58:59], v[58:59], v[88:89] op_sel_hi:[1,0]
	v_pk_mul_f32 v[60:61], v[60:61], v[88:89] op_sel_hi:[1,0]
	v_pk_mul_f32 v[58:59], v[58:59], v[14:15]
	v_pk_mul_f32 v[60:61], v[60:61], v[16:17]
	global_store_dwordx4 v74, v[58:61], s[36:37] offset:16
	v_pk_mul_f32 v[62:63], v[62:63], v[88:89] op_sel_hi:[1,0]
	v_pk_mul_f32 v[64:65], v[64:65], v[88:89] op_sel_hi:[1,0]
	v_pk_mul_f32 v[62:63], v[62:63], v[26:27]
	v_pk_mul_f32 v[64:65], v[64:65], v[28:29]
	global_store_dwordx4 v74, v[62:65], s[36:37] offset:2048
	v_pk_mul_f32 v[66:67], v[66:67], v[88:89] op_sel_hi:[1,0]
	v_pk_mul_f32 v[68:69], v[68:69], v[88:89] op_sel_hi:[1,0]
	v_pk_mul_f32 v[66:67], v[66:67], v[38:39]
	v_pk_mul_f32 v[68:69], v[68:69], v[40:41]
	global_store_dwordx4 v74, v[66:69], s[36:37] offset:2064
	s_nop 1
	v_lshlrev_b32_e32 v54, 16, v100
	v_and_b32_e32 v55, 0xffff0000, v100
	v_lshlrev_b32_e32 v56, 16, v101
	v_and_b32_e32 v57, 0xffff0000, v101
	v_lshlrev_b32_e32 v58, 16, v102
	v_and_b32_e32 v59, 0xffff0000, v102
	v_lshlrev_b32_e32 v60, 16, v103
	v_and_b32_e32 v61, 0xffff0000, v103
	v_lshlrev_b32_e32 v62, 16, v104
	v_and_b32_e32 v63, 0xffff0000, v104
	v_lshlrev_b32_e32 v64, 16, v105
	v_and_b32_e32 v65, 0xffff0000, v105
	v_lshlrev_b32_e32 v66, 16, v106
	v_and_b32_e32 v67, 0xffff0000, v106
	v_lshlrev_b32_e32 v68, 16, v107
	v_and_b32_e32 v69, 0xffff0000, v107
	s_add_i32 s8, s8, s12
	s_add_u32 s36, s36, s3
	s_addc_u32 s37, s37, 0
	s_cmp_lt_i32 s8, 0x8000
	s_cbranch_scc0 .Lnf_done
	s_branch .Lnf_loopA

; __device__ __forceinline__ unsigned pk2(float lo, float hi) { const f32x2_t v = {lo, hi}; return __builtin_bit_cast(unsigned, __builtin_convertvector(v, bf16x2_t)); }
;     const int r_beg = gw, r_end = nrows;
;     int cur_mod = -1; f32x4 gs[4], shv[4], vn[4];
; #pragma unroll
;     for (int j = 0; j < 4; ++j) { gs[j] = (f32x4){0.f, 0.f, 0.f, 0.f}; shv[j] = gs[j]; vn[j] = gs[j]; }
;     if (r_beg < r_end) {
; #pragma unroll
;         for (int j = 0; j < 4; ++j) vn[j] = ld_row4(srcL, xb_in, srcC, r_beg, lane + 64 * j); }
; #pragma unroll 1
;     for (int row = r_beg; row < r_end; row += NGW) {
;         const bool isc = row >= ML; const int mod = isc ? 4 : (row >> 13);
;         f32x4 v[4];
; #pragma unroll
;         for (int j = 0; j < 4; ++j) v[j] = vn[j];
;         if (row + NGW < r_end) { const int rn = row + NGW;
; #pragma unroll
;             for (int j = 0; j < 4; ++j) vn[j] = ld_row4(srcL, xb_in, srcC, rn, lane + 64 * j); }
;         if (xb_out && !isc) {
; #pragma unroll
;             for (int j = 0; j < 4; ++j) { u32x2 w; w.x = pk2(v[j].x, v[j].y); w.y = pk2(v[j].z, v[j].w); ((u32x2*)(xb_out + (size_t)row * DM))[lane + 64 * j] = w; } }
;         if (mod != cur_mod) { cur_mod = mod; const float* shp = mods_l + mod * 6144 + sh_off; const float* scp = mods_l + mod * 6144 + sc_off;
; #pragma unroll
;             for (int j = 0; j < 4; ++j) { gs[j] = ((const f32x4*)gam)[lane + 64 * j] * (((const f32x4*)scp)[lane + 64 * j] + 1.0f); shv[j] = ((const f32x4*)shp)[lane + 64 * j]; } }
.Ln4_begin:
	v_lshlrev_b32_e32 v86, 4, v249
	v_lshlrev_b32_e32 v74, 5, v249
	v_lshlrev_b32_e32 v3, 2, v249
	v_xor_b32_e32 v1, 4, v3
	v_xor_b32_e32 v71, 8, v3
	v_xor_b32_e32 v73, 16, v3
	v_xor_b32_e32 v96, 32, v3
	v_xor_b32_e32 v97, 64, v3
	v_xor_b32_e32 v98, 0x80, v3
	s_load_dwordx2 s[0:1], s[28:29], 0x68
	s_lshl_b32 s6, s22, 12
	s_waitcnt lgkmcnt(0)
	s_add_u32 s0, s0, s6
	s_addc_u32 s1, s1, 0
	s_mov_b32 s3, -1
	s_mov_b32 s8, s10
	s_lshl_b32 s13, s12, 11
	s_cmp_lt_i32 s8, 0x8000
	s_cbranch_scc0 .Ln4_ctx
	s_ashr_i32 s11, s10, 31
	s_lshl_b64 s[6:7], s[10:11], 11
	s_add_u32 s34, s30, s6
	s_addc_u32 s35, s31, s7
	s_add_u32 s36, s75, s6
	s_addc_u32 s37, s76, s7
	s_mov_b32 s46, s10
	global_load_dwordx4 v[100:103], v86, s[34:35]
	global_load_dwordx4 v[104:107], v86, s[34:35] offset:1024
	s_add_i32 s11, s46, s12
	s_cmp_lt_i32 s11, 0x8000
	s_cselect_b32 s46, s11, s46
	s_cselect_b32 s11, s13, 0
	s_add_u32 s34, s34, s11
	s_addc_u32 s35, s35, 0
	global_load_dwordx4 v[108:111], v86, s[34:35]
	global_load_dwordx4 v[112:115], v86, s[34:35] offset:1024
	s_add_i32 s11, s46, s12
	s_cmp_lt_i32 s11, 0x8000
	s_cselect_b32 s46, s11, s46
	s_cselect_b32 s11, s13, 0
	s_add_u32 s34, s34, s11
	s_addc_u32 s35, s35, 0
	s_waitcnt vmcnt(2)
	v_lshlrev_b32_e32 v54, 16, v100
	v_and_b32_e32 v55, 0xffff0000, v100
	v_lshlrev_b32_e32 v56, 16, v101
	v_and_b32_e32 v57, 0xffff0000, v101
	v_lshlrev_b32_e32 v58, 16, v102
	v_and_b32_e32 v59, 0xffff0000, v102
	v_lshlrev_b32_e32 v60, 16, v103
	v_and_b32_e32 v61, 0xffff0000, v103
	v_lshlrev_b32_e32 v62, 16, v104
	v_and_b32_e32 v63, 0xffff0000, v104
	v_lshlrev_b32_e32 v64, 16, v105
	v_and_b32_e32 v65, 0xffff0000, v105
	v_lshlrev_b32_e32 v66, 16, v106
	v_and_b32_e32 v67, 0xffff0000, v106
	v_lshlrev_b32_e32 v68, 16, v107
	v_and_b32_e32 v69, 0xffff0000, v107
.Ln4_loopA:
	s_ashr_i32 s11, s8, 13
	s_cmp_eq_u32 s11, s3
	s_cbranch_scc1 .Ln4_modokA
	s_mov_b32 s3, s11
	s_mul_i32 s11, s11, 0x6000
	s_add_u32 s42, s80, s11
	s_addc_u32 s43, s81, 0
	s_add_u32 s54, s42, 0x3000
	s_addc_u32 s55, s43, 0
	s_add_u32 s42, s42, 0x4000
	s_addc_u32 s43, s43, 0
	global_load_dwordx4 v[10:13], v74, s[42:43]
	global_load_dwordx4 v[18:21], v74, s[42:43] offset:16
	global_load_dwordx4 v[30:33], v74, s[42:43] offset:2048
	global_load_dwordx4 v[46:49], v74, s[42:43] offset:2064
	global_load_dwordx4 v[6:9], v74, s[0:1]
	global_load_dwordx4 v[14:17], v74, s[0:1] offset:16
	global_load_dwordx4 v[26:29], v74, s[0:1] offset:2048
	global_load_dwordx4 v[38:41], v74, s[0:1] offset:2064
	s_waitcnt vmcnt(0)
	v_pk_add_f32 v[10:11], v[10:11], 1.0 op_sel_hi:[1,0]
	v_pk_add_f32 v[12:13], v[12:13], 1.0 op_sel_hi:[1,0]
	v_pk_mul_f32 v[6:7], v[6:7], v[10:11]
	v_pk_mul_f32 v[8:9], v[8:9], v[12:13]
	v_pk_add_f32 v[18:19], v[18:19], 1.0 op_sel_hi:[1,0]
	v_pk_add_f32 v[20:21], v[20:21], 1.0 op_sel_hi:[1,0]
	v_pk_mul_f32 v[14:15], v[14:15], v[18:19]
	v_pk_mul_f32 v[16:17], v[16:17], v[20:21]
	v_pk_add_f32 v[30:31], v[30:31], 1.0 op_sel_hi:[1,0]
	v_pk_add_f32 v[32:33], v[32:33], 1.0 op_sel_hi:[1,0]
	v_pk_mul_f32 v[26:27], v[26:27], v[30:31]
	v_pk_mul_f32 v[28:29], v[28:29], v[32:33]
	v_pk_add_f32 v[46:47], v[46:47], 1.0 op_sel_hi:[1,0]
	v_pk_add_f32 v[48:49], v[48:49], 1.0 op_sel_hi:[1,0]
	v_pk_mul_f32 v[38:39], v[38:39], v[46:47]
	v_pk_mul_f32 v[40:41], v[40:41], v[48:49]
	global_load_dwordx4 v[10:13], v74, s[54:55]
	global_load_dwordx4 v[18:21], v74, s[54:55] offset:16
	global_load_dwordx4 v[30:33], v74, s[54:55] offset:2048
	global_load_dwordx4 v[46:49], v74, s[54:55] offset:2064

;     ...
;         if (mod != cur_mod) { cur_mod = mod; const float* shp = mods_l + mod * 6144 + sh_off; const float* scp = mods_l + mod * 6144 + sc_off;
; #pragma unroll
;             for (int j = 0; j < 4; ++j) { gs[j] = ((const f32x4*)gam)[lane + 64 * j] * (((const f32x4*)scp)[lane + 64 * j] + 1.0f); shv[j] = ((const f32x4*)shp)[lane + 64 * j]; } }
;         if (isc && npart > 0) {
;             for (int ks = 0; ks < npart; ++ks) { const f32x4* pp = (const f32x4*)(part + ((size_t)ks * MC + (row - ML)) * DM);
; #pragma unroll
;                 for (int j = 0; j < 4; ++j) v[j] += pp[lane + 64 * j]; }
; #pragma unroll
;             for (int j = 0; j < 4; ++j) ((f32x4*)(srcC + (size_t)(row - ML) * DM))[lane + 64 * j] = v[j];
.Ln4_ctxloop:
	s_add_u32 s54, s80, 0x1b000
	s_addc_u32 s55, s81, 0
	s_add_u32 s42, s80, 0x1c000
	s_addc_u32 s43, s81, 0
	global_load_dwordx4 v[10:13], v74, s[42:43]
	global_load_dwordx4 v[18:21], v74, s[42:43] offset:16
	global_load_dwordx4 v[30:33], v74, s[42:43] offset:2048
	global_load_dwordx4 v[46:49], v74, s[42:43] offset:2064
	global_load_dwordx4 v[6:9], v74, s[0:1]
	global_load_dwordx4 v[14:17], v74, s[0:1] offset:16
	global_load_dwordx4 v[26:29], v74, s[0:1] offset:2048
	global_load_dwordx4 v[38:41], v74, s[0:1] offset:2064
	s_add_i32 s6, s8, 0xffff8000
	s_mov_b32 s7, 0
	s_lshl_b64 s[6:7], s[6:7], 12
	s_add_u32 s84, s20, s6
	s_addc_u32 s85, s21, s7
	global_load_dwordx4 v[54:57], v74, s[84:85]
	global_load_dwordx4 v[58:61], v74, s[84:85] offset:16
	global_load_dwordx4 v[62:65], v74, s[84:85] offset:2048
	global_load_dwordx4 v[66:69], v74, s[84:85] offset:2064
	s_waitcnt vmcnt(0)
	v_pk_add_f32 v[10:11], v[10:11], 1.0 op_sel_hi:[1,0]
	v_pk_add_f32 v[12:13], v[12:13], 1.0 op_sel_hi:[1,0]
	v_pk_mul_f32 v[6:7], v[6:7], v[10:11]
	v_pk_mul_f32 v[8:9], v[8:9], v[12:13]
	v_pk_add_f32 v[18:19], v[18:19], 1.0 op_sel_hi:[1,0]
	v_pk_add_f32 v[20:21], v[20:21], 1.0 op_sel_hi:[1,0]
	v_pk_mul_f32 v[14:15], v[14:15], v[18:19]
	v_pk_mul_f32 v[16:17], v[16:17], v[20:21]
	v_pk_add_f32 v[30:31], v[30:31], 1.0 op_sel_hi:[1,0]
	v_pk_add_f32 v[32:33], v[32:33], 1.0 op_sel_hi:[1,0]
	v_pk_mul_f32 v[26:27], v[26:27], v[30:31]
	v_pk_mul_f32 v[28:29], v[28:29], v[32:33]
	v_pk_add_f32 v[46:47], v[46:47], 1.0 op_sel_hi:[1,0]
	v_pk_add_f32 v[48:49], v[48:49], 1.0 op_sel_hi:[1,0]
	v_pk_mul_f32 v[38:39], v[38:39], v[46:47]
	v_pk_mul_f32 v[40:41], v[40:41], v[48:49]
	global_load_dwordx4 v[10:13], v74, s[54:55]
	global_load_dwordx4 v[18:21], v74, s[54:55] offset:16
	global_load_dwordx4 v[30:33], v74, s[54:55] offset:2048
	global_load_dwordx4 v[46:49], v74, s[54:55] offset:2064
	s_add_u32 s86, s16, s6
	s_addc_u32 s87, s17, s7
	s_add_u32 s42, s86, 0x0
	s_addc_u32 s43, s87, 0
	global_load_dwordx4 v[116:119], v74, s[42:43]
	global_load_dwordx4 v[120:123], v74, s[42:43] offset:16
	global_load_dwordx4 v[124:127], v74, s[42:43] offset:2048
	global_load_dwordx4 v[128:131], v74, s[42:43] offset:2064
	s_add_u32 s42, s86, 0x400000
	s_addc_u32 s43, s87, 0
	global_load_dwordx4 v[132:135], v74, s[42:43]
	global_load_dwordx4 v[136:139], v74, s[42:43] offset:16
	global_load_dwordx4 v[140:143], v74, s[42:43] offset:2048
	global_load_dwordx4 v[144:147], v74, s[42:43] offset:2064
	s_add_u32 s42, s86, 0x800000
	s_addc_u32 s43, s87, 0
	global_load_dwordx4 v[148:151], v74, s[42:43]
	global_load_dwordx4 v[152:155], v74, s[42:43] offset:16
	global_load_dwordx4 v[156:159], v74, s[42:43] offset:2048
	global_load_dwordx4 v[160:163], v74, s[42:43] offset:2064
	s_add_u32 s42, s86, 0xc00000
	s_addc_u32 s43, s87, 0
	global_load_dwordx4 v[164:167], v74, s[42:43]
	global_load_dwordx4 v[168:171], v74, s[42:43] offset:16
	global_load_dwordx4 v[172:175], v74, s[42:43] offset:2048
	global_load_dwordx4 v[176:179], v74, s[42:43] offset:2064
	s_waitcnt vmcnt(0)
; __device__ __forceinline__ unsigned pk2(float lo, float hi) { const f32x2_t v = {lo, hi}; return __builtin_bit_cast(unsigned, __builtin_convertvector(v, bf16x2_t)); }
;     ...
;         if (isc && npart > 0) {
;             for (int ks = 0; ks < npart; ++ks) { const f32x4* pp = (const f32x4*)(part + ((size_t)ks * MC + (row - ML)) * DM);
; #pragma unroll
;                 for (int j = 0; j < 4; ++j) v[j] += pp[lane + 64 * j]; }
; #pragma unroll
;             for (int j = 0; j < 4; ++j) ((f32x4*)(srcC + (size_t)(row - ML) * DM))[lane + 64 * j] = v[j];
;         }
;         float s = 0.f;
; #pragma unroll
;         for (int j = 0; j < 4; ++j) s += (v[j].x * v[j].x + v[j].y * v[j].y) + (v[j].z * v[j].z + v[j].w * v[j].w);
;         s = wave_sum(s, lane); const float rstd = 1.0f / sqrtf(s * (1.0f / DM) + 1e-6f);
; #pragma unroll
;         for (int j = 0; j < 4; ++j) { const f32x4 y = v[j] * rstd * gs[j] + shv[j]; u32x2 w; w.x = pk2(y.x, y.y); w.y = pk2(y.z, y.w);
;             ((u32x2*)(H + (size_t)row * DM))[lane + 64 * j] = w; }
	v_pk_add_f32 v[54:55], v[54:55], v[116:117]
	v_pk_add_f32 v[56:57], v[56:57], v[118:119]
	v_pk_add_f32 v[58:59], v[58:59], v[120:121]
	v_pk_add_f32 v[60:61], v[60:61], v[122:123]
	v_pk_add_f32 v[62:63], v[62:63], v[124:125]
	v_pk_add_f32 v[64:65], v[64:65], v[126:127]
	v_pk_add_f32 v[66:67], v[66:67], v[128:129]
	v_pk_add_f32 v[68:69], v[68:69], v[130:131]
	v_pk_add_f32 v[54:55], v[54:55], v[132:133]
	v_pk_add_f32 v[56:57], v[56:57], v[134:135]
	v_pk_add_f32 v[58:59], v[58:59], v[136:137]
	v_pk_add_f32 v[60:61], v[60:61], v[138:139]
	v_pk_add_f32 v[62:63], v[62:63], v[140:141]
	v_pk_add_f32 v[64:65], v[64:65], v[142:143]
	v_pk_add_f32 v[66:67], v[66:67], v[144:145]
	v_pk_add_f32 v[68:69], v[68:69], v[146:147]
	v_pk_add_f32 v[54:55], v[54:55], v[148:149]
	v_pk_add_f32 v[56:57], v[56:57], v[150:151]
	v_pk_add_f32 v[58:59], v[58:59], v[152:153]
	v_pk_add_f32 v[60:61], v[60:61], v[154:155]
	v_pk_add_f32 v[62:63], v[62:63], v[156:157]
	v_pk_add_f32 v[64:65], v[64:65], v[158:159]
	v_pk_add_f32 v[66:67], v[66:67], v[160:161]
	v_pk_add_f32 v[68:69], v[68:69], v[162:163]
	v_pk_add_f32 v[54:55], v[54:55], v[164:165]
	v_pk_add_f32 v[56:57], v[56:57], v[166:167]
	v_pk_add_f32 v[58:59], v[58:59], v[168:169]
	v_pk_add_f32 v[60:61], v[60:61], v[170:171]
	v_pk_add_f32 v[62:63], v[62:63], v[172:173]
	v_pk_add_f32 v[64:65], v[64:65], v[174:175]
	v_pk_add_f32 v[66:67], v[66:67], v[176:177]
	v_pk_add_f32 v[68:69], v[68:69], v[178:179]
	global_store_dwordx4 v74, v[54:57], s[84:85]
	global_store_dwordx4 v74, v[58:61], s[84:85] offset:16
	global_store_dwordx4 v74, v[62:65], s[84:85] offset:2048
	global_store_dwordx4 v74, v[66:69], s[84:85] offset:2064
	s_ashr_i32 s11, s8, 31
	s_mov_b32 s6, s8
	s_mov_b32 s7, s11
	s_lshl_b64 s[6:7], s[6:7], 11
	s_add_u32 s36, s75, s6
	s_addc_u32 s37, s76, s7
	v_pk_mul_f32 v[90:91], v[56:57], v[56:57]
	v_pk_mul_f32 v[92:93], v[54:55], v[54:55]
	v_pk_mul_f32 v[4:5], v[60:61], v[60:61]
	v_pk_mul_f32 v[88:89], v[58:59], v[58:59]
	v_pk_mov_b32 v[94:95], v[92:93], v[90:91] op_sel:[1,0]
	v_mov_b32_e32 v93, v91
	v_pk_add_f32 v[90:91], v[94:95], v[92:93]
	v_pk_mov_b32 v[92:93], v[88:89], v[4:5] op_sel:[1,0]
	v_mov_b32_e32 v89, v5
	v_pk_add_f32 v[4:5], v[92:93], v[88:89]
	v_pk_add_f32 v[90:91], v[90:91], v[90:91] op_sel_hi:[0,1]
	v_pk_add_f32 v[4:5], v[4:5], v[4:5] op_sel_hi:[0,1]
	v_mul_f32_e32 v4, v62, v62
	v_pk_fma_f32 v[88:89], v[62:63], v[62:63], v[4:5] op_sel_hi:[1,1,0]
	v_mul_f32_e32 v4, v64, v64
	v_pk_fma_f32 v[92:93], v[64:65], v[64:65], v[4:5] op_sel_hi:[1,1,0]
	v_mul_f32_e32 v88, v66, v66
	v_mul_f32_e32 v92, v67, v67
	v_mul_f32_e32 v90, v68, v68
	v_mul_f32_e32 v4, v69, v69
	v_pk_add_f32 v[88:89], v[88:89], v[92:93]
	v_pk_add_f32 v[4:5], v[90:91], v[4:5]
	v_pk_add_f32 v[4:5], v[88:89], v[4:5]
	s_nop 0
	v_add_f32_e32 v3, v4, v5
	ds_bpermute_b32 v4, v1, v3
	s_waitcnt lgkmcnt(0)
	v_add_f32_e32 v3, v3, v4
	ds_bpermute_b32 v4, v71, v3
	s_waitcnt lgkmcnt(0)
	v_add_f32_e32 v3, v3, v4
	ds_bpermute_b32 v4, v73, v3
	s_waitcnt lgkmcnt(0)
	v_add_f32_e32 v3, v3, v4
	ds_bpermute_b32 v4, v96, v3
	s_waitcnt lgkmcnt(0)
	v_add_f32_e32 v3, v3, v4
	ds_bpermute_b32 v4, v97, v3
	s_waitcnt lgkmcnt(0)
	v_add_f32_e32 v3, v3, v4
	ds_bpermute_b32 v4, v98, v3
	s_waitcnt lgkmcnt(0)
	v_add_f32_e32 v3, v3, v4
	v_fmamk_f32 v3, v3, 0x3a800000, v238
	v_mul_f32_e32 v4, 0x4f800000, v3
	v_cmp_gt_f32_e32 vcc, s58, v3
	s_nop 1
	v_cndmask_b32_e32 v3, v3, v4, vcc
	v_sqrt_f32_e32 v4, v3
	s_nop 0
	v_add_u32_e32 v5, -1, v4
	v_add_u32_e32 v75, 1, v4
	v_fma_f32 v88, -v5, v4, v3
	v_fma_f32 v89, -v75, v4, v3
	v_cmp_ge_f32_e64 s[4:5], 0, v88
	s_nop 1
	v_cndmask_b32_e64 v4, v4, v5, s[4:5]
	v_cmp_lt_f32_e64 s[4:5], 0, v89
	s_nop 1
	v_cndmask_b32_e64 v4, v4, v75, s[4:5]
	v_mul_f32_e32 v5, 0x37800000, v4
	v_cndmask_b32_e32 v4, v4, v5, vcc
	v_cmp_class_f32_e32 vcc, v3, v248
	s_nop 1
	v_cndmask_b32_e32 v3, v4, v3, vcc
	v_div_scale_f32 v75, s[4:5], v3, v3, 1.0
	v_rcp_f32_e32 v88, v75
	v_div_scale_f32 v89, vcc, 1.0, v3, 1.0
	v_fma_f32 v90, -v75, v88, 1.0
	v_fmac_f32_e32 v88, v90, v88
	v_mul_f32_e32 v90, v89, v88
	v_fma_f32 v91, -v75, v90, v89
	v_fmac_f32_e32 v90, v91, v88
	v_fma_f32 v75, -v75, v90, v89
	v_div_fmas_f32 v75, v75, v88, v90
	v_div_fixup_f32 v88, v75, v3, 1.0
	v_pk_mul_f32 v[54:55], v[54:55], v[88:89] op_sel_hi:[1,0]
	v_pk_mul_f32 v[56:57], v[56:57], v[88:89] op_sel_hi:[1,0]
	v_pk_fma_f32 v[54:55], v[6:7], v[54:55], v[10:11]
	v_pk_fma_f32 v[56:57], v[8:9], v[56:57], v[12:13]
	v_cvt_pk_bf16_f32 v120, v54, v55
	v_cvt_pk_bf16_f32 v121, v56, v57
	v_pk_mul_f32 v[58:59], v[58:59], v[88:89] op_sel_hi:[1,0]
	v_pk_mul_f32 v[60:61], v[60:61], v[88:89] op_sel_hi:[1,0]
	v_pk_fma_f32 v[58:59], v[14:15], v[58:59], v[18:19]
	v_pk_fma_f32 v[60:61], v[16:17], v[60:61], v[20:21]
	v_cvt_pk_bf16_f32 v122, v58, v59
	v_cvt_pk_bf16_f32 v123, v60, v61
	global_store_dwordx4 v86, v[120:123], s[36:37]
	v_pk_mul_f32 v[62:63], v[62:63], v[88:89] op_sel_hi:[1,0]
	v_pk_mul_f32 v[64:65], v[64:65], v[88:89] op_sel_hi:[1,0]
	v_pk_fma_f32 v[62:63], v[26:27], v[62:63], v[30:31]
	v_pk_fma_f32 v[64:65], v[28:29], v[64:65], v[32:33]
	v_cvt_pk_bf16_f32 v124, v62, v63
	v_cvt_pk_bf16_f32 v125, v64, v65
	v_pk_mul_f32 v[66:67], v[66:67], v[88:89] op_sel_hi:[1,0]
	v_pk_mul_f32 v[68:69], v[68:69], v[88:89] op_sel_hi:[1,0]
	v_pk_fma_f32 v[66:67], v[38:39], v[66:67], v[46:47]
	v_pk_fma_f32 v[68:69], v[40:41], v[68:69], v[48:49]
	v_cvt_pk_bf16_f32 v126, v66, v67
	v_cvt_pk_bf16_f32 v127, v68, v69
	global_store_dwordx4 v86, v[124:127], s[36:37] offset:1024
	s_add_i32 s8, s8, s12
	s_cmp_lt_i32 s8, s77
	s_cbranch_scc1 .Ln4_ctxloop
